# SEC7/SEC8 gate-sigmoid epilogues hand-written with packed f32 mul/add (34 VALU per 8 elements instead of ~47), on top of the peeled K step
# baseline (speedup 1.0000x reference)
.Lsec78_a:
	s_mov_b32 s1, 0x9ce6000
	s_cmp_eq_u32 s2, 8
	s_cselect_b32 s1, 0xbd25800, s1
	s_lshl_b32 s0, s48, 8
	v_add_u32_e32 v152, s0, v241
	v_lshlrev_b32_e32 v152, 11, v152
	v_or_b32_e32 v132, s74, v178
	v_lshl_add_u32 v152, v132, 1, v152
	s_add_u32 s4, s94, s1
	s_addc_u32 s5, s95, 0
	v_mov_b32_e32 v148, 0xbfb8aa3b
	v_mov_b32_e32 v149, 0xbfb8aa3b
	v_mov_b32_e32 v150, 1.0
	v_mov_b32_e32 v151, 1.0
	v_pk_mul_f32 v[132:133], v[128:129], v[164:165] op_sel_hi:[1,0]
	v_pk_mul_f32 v[134:135], v[130:131], v[164:165] op_sel_hi:[1,0]
	v_pk_mul_f32 v[136:137], v[124:125], v[164:165] op_sel_hi:[1,0]
	v_pk_mul_f32 v[138:139], v[126:127], v[164:165] op_sel_hi:[1,0]
	v_pk_mul_f32 v[140:141], v[132:133], v[148:149]
	v_pk_mul_f32 v[142:143], v[134:135], v[148:149]
	v_pk_mul_f32 v[144:145], v[136:137], v[148:149]
	v_pk_mul_f32 v[146:147], v[138:139], v[148:149]
	v_exp_f32_e32 v140, v140
	v_exp_f32_e32 v141, v141
	v_exp_f32_e32 v142, v142
	v_exp_f32_e32 v143, v143
	v_exp_f32_e32 v144, v144
	v_exp_f32_e32 v145, v145
	v_exp_f32_e32 v146, v146
	v_exp_f32_e32 v147, v147
	v_pk_add_f32 v[140:141], v[140:141], v[150:151]
	v_pk_add_f32 v[142:143], v[142:143], v[150:151]
	v_pk_add_f32 v[144:145], v[144:145], v[150:151]
	v_pk_add_f32 v[146:147], v[146:147], v[150:151]
	v_rcp_f32_e32 v140, v140
	v_rcp_f32_e32 v141, v141
	v_rcp_f32_e32 v142, v142
	v_rcp_f32_e32 v143, v143
	v_rcp_f32_e32 v144, v144
	v_rcp_f32_e32 v145, v145
	v_rcp_f32_e32 v146, v146
	v_rcp_f32_e32 v147, v147
	v_cvt_pk_bf16_f32 v132, v140, v141
	v_cvt_pk_bf16_f32 v133, v142, v143
	v_cvt_pk_bf16_f32 v134, v144, v145
	v_cvt_pk_bf16_f32 v135, v146, v147
	global_store_dwordx4 v152, v[132:135], s[4:5] offset:512
	s_add_u32 s4, s4, 0x8000
	s_addc_u32 s5, s5, 0
	v_pk_mul_f32 v[132:133], v[120:121], v[164:165] op_sel:[0,1] op_sel_hi:[1,1]
	v_pk_mul_f32 v[134:135], v[122:123], v[164:165] op_sel:[0,1] op_sel_hi:[1,1]
	v_pk_mul_f32 v[136:137], v[116:117], v[164:165] op_sel:[0,1] op_sel_hi:[1,1]
	v_pk_mul_f32 v[138:139], v[118:119], v[164:165] op_sel:[0,1] op_sel_hi:[1,1]
	v_pk_mul_f32 v[140:141], v[132:133], v[148:149]
	v_pk_mul_f32 v[142:143], v[134:135], v[148:149]
	v_pk_mul_f32 v[144:145], v[136:137], v[148:149]
	v_pk_mul_f32 v[146:147], v[138:139], v[148:149]
	v_exp_f32_e32 v140, v140
	v_exp_f32_e32 v141, v141
	v_exp_f32_e32 v142, v142
	v_exp_f32_e32 v143, v143
	v_exp_f32_e32 v144, v144
	v_exp_f32_e32 v145, v145
	v_exp_f32_e32 v146, v146
	v_exp_f32_e32 v147, v147
	v_pk_add_f32 v[140:141], v[140:141], v[150:151]
	v_pk_add_f32 v[142:143], v[142:143], v[150:151]
	v_pk_add_f32 v[144:145], v[144:145], v[150:151]
	v_pk_add_f32 v[146:147], v[146:147], v[150:151]
	v_rcp_f32_e32 v140, v140
	v_rcp_f32_e32 v141, v141
	v_rcp_f32_e32 v142, v142
	v_rcp_f32_e32 v143, v143
	v_rcp_f32_e32 v144, v144
	v_rcp_f32_e32 v145, v145
	v_rcp_f32_e32 v146, v146
	v_rcp_f32_e32 v147, v147
	v_cvt_pk_bf16_f32 v132, v140, v141
	v_cvt_pk_bf16_f32 v133, v142, v143
	v_cvt_pk_bf16_f32 v134, v144, v145
	v_cvt_pk_bf16_f32 v135, v146, v147
	global_store_dwordx4 v152, v[132:135], s[4:5] offset:512
	s_add_u32 s4, s4, 0x8000
	s_addc_u32 s5, s5, 0
	v_pk_mul_f32 v[132:133], v[112:113], v[166:167] op_sel_hi:[1,0]
	v_pk_mul_f32 v[134:135], v[114:115], v[166:167] op_sel_hi:[1,0]
	v_pk_mul_f32 v[136:137], v[108:109], v[166:167] op_sel_hi:[1,0]
	v_pk_mul_f32 v[138:139], v[110:111], v[166:167] op_sel_hi:[1,0]
	v_pk_mul_f32 v[140:141], v[132:133], v[148:149]
	v_pk_mul_f32 v[142:143], v[134:135], v[148:149]
	v_pk_mul_f32 v[144:145], v[136:137], v[148:149]
	v_pk_mul_f32 v[146:147], v[138:139], v[148:149]
	v_exp_f32_e32 v140, v140
	v_exp_f32_e32 v141, v141
	v_exp_f32_e32 v142, v142
	v_exp_f32_e32 v143, v143
	v_exp_f32_e32 v144, v144
	v_exp_f32_e32 v145, v145
	v_exp_f32_e32 v146, v146
	v_exp_f32_e32 v147, v147
	v_pk_add_f32 v[140:141], v[140:141], v[150:151]
	v_pk_add_f32 v[142:143], v[142:143], v[150:151]
	v_pk_add_f32 v[144:145], v[144:145], v[150:151]
	v_pk_add_f32 v[146:147], v[146:147], v[150:151]
	v_rcp_f32_e32 v140, v140
	v_rcp_f32_e32 v141, v141
	v_rcp_f32_e32 v142, v142
	v_rcp_f32_e32 v143, v143
	v_rcp_f32_e32 v144, v144
	v_rcp_f32_e32 v145, v145
	v_rcp_f32_e32 v146, v146
	v_rcp_f32_e32 v147, v147
	v_cvt_pk_bf16_f32 v132, v140, v141
	v_cvt_pk_bf16_f32 v133, v142, v143
	v_cvt_pk_bf16_f32 v134, v144, v145
	v_cvt_pk_bf16_f32 v135, v146, v147
	global_store_dwordx4 v152, v[132:135], s[4:5] offset:512
	s_add_u32 s4, s4, 0x8000
	s_addc_u32 s5, s5, 0
	v_pk_mul_f32 v[132:133], v[104:105], v[166:167] op_sel:[0,1] op_sel_hi:[1,1]
	v_pk_mul_f32 v[134:135], v[106:107], v[166:167] op_sel:[0,1] op_sel_hi:[1,1]
	v_pk_mul_f32 v[136:137], v[100:101], v[166:167] op_sel:[0,1] op_sel_hi:[1,1]
	v_pk_mul_f32 v[138:139], v[102:103], v[166:167] op_sel:[0,1] op_sel_hi:[1,1]
	v_pk_mul_f32 v[140:141], v[132:133], v[148:149]
	v_pk_mul_f32 v[142:143], v[134:135], v[148:149]
	v_pk_mul_f32 v[144:145], v[136:137], v[148:149]
	v_pk_mul_f32 v[146:147], v[138:139], v[148:149]
	v_exp_f32_e32 v140, v140
	v_exp_f32_e32 v141, v141
	v_exp_f32_e32 v142, v142
	v_exp_f32_e32 v143, v143
	v_exp_f32_e32 v144, v144
	v_exp_f32_e32 v145, v145
	v_exp_f32_e32 v146, v146
	v_exp_f32_e32 v147, v147
	v_pk_add_f32 v[140:141], v[140:141], v[150:151]
	v_pk_add_f32 v[142:143], v[142:143], v[150:151]
	v_pk_add_f32 v[144:145], v[144:145], v[150:151]
	v_pk_add_f32 v[146:147], v[146:147], v[150:151]
	v_rcp_f32_e32 v140, v140
	v_rcp_f32_e32 v141, v141
	v_rcp_f32_e32 v142, v142
	v_rcp_f32_e32 v143, v143
	v_rcp_f32_e32 v144, v144
	v_rcp_f32_e32 v145, v145
	v_rcp_f32_e32 v146, v146
	v_rcp_f32_e32 v147, v147
	v_cvt_pk_bf16_f32 v132, v140, v141
	v_cvt_pk_bf16_f32 v133, v142, v143
	v_cvt_pk_bf16_f32 v134, v144, v145
	v_cvt_pk_bf16_f32 v135, v146, v147
	global_store_dwordx4 v152, v[132:135], s[4:5] offset:512
	s_add_u32 s4, s4, 0x28000
	s_addc_u32 s5, s5, 0
	s_cmp_eq_u32 s48, 64
	s_cbranch_scc1 .Lsig_a_done
	v_pk_mul_f32 v[132:133], v[96:97], v[246:247] op_sel_hi:[1,0]
	v_pk_mul_f32 v[134:135], v[98:99], v[246:247] op_sel_hi:[1,0]
	v_pk_mul_f32 v[136:137], v[92:93], v[246:247] op_sel_hi:[1,0]
	v_pk_mul_f32 v[138:139], v[94:95], v[246:247] op_sel_hi:[1,0]
	v_pk_mul_f32 v[140:141], v[132:133], v[148:149]
	v_pk_mul_f32 v[142:143], v[134:135], v[148:149]
	v_pk_mul_f32 v[144:145], v[136:137], v[148:149]
	v_pk_mul_f32 v[146:147], v[138:139], v[148:149]
	v_exp_f32_e32 v140, v140
	v_exp_f32_e32 v141, v141
	v_exp_f32_e32 v142, v142
	v_exp_f32_e32 v143, v143
	v_exp_f32_e32 v144, v144
	v_exp_f32_e32 v145, v145
	v_exp_f32_e32 v146, v146
	v_exp_f32_e32 v147, v147
	v_pk_add_f32 v[140:141], v[140:141], v[150:151]
	v_pk_add_f32 v[142:143], v[142:143], v[150:151]
	v_pk_add_f32 v[144:145], v[144:145], v[150:151]
	v_pk_add_f32 v[146:147], v[146:147], v[150:151]
	v_rcp_f32_e32 v140, v140
	v_rcp_f32_e32 v141, v141
	v_rcp_f32_e32 v142, v142
	v_rcp_f32_e32 v143, v143
	v_rcp_f32_e32 v144, v144
	v_rcp_f32_e32 v145, v145
	v_rcp_f32_e32 v146, v146
	v_rcp_f32_e32 v147, v147
	v_cvt_pk_bf16_f32 v132, v140, v141
	v_cvt_pk_bf16_f32 v133, v142, v143
	v_cvt_pk_bf16_f32 v134, v144, v145
	v_cvt_pk_bf16_f32 v135, v146, v147
	global_store_dwordx4 v152, v[132:135], s[4:5] offset:512
	s_add_u32 s4, s4, 0x8000
	s_addc_u32 s5, s5, 0
	v_pk_mul_f32 v[132:133], v[88:89], v[246:247] op_sel:[0,1] op_sel_hi:[1,1]
	v_pk_mul_f32 v[134:135], v[90:91], v[246:247] op_sel:[0,1] op_sel_hi:[1,1]
	v_pk_mul_f32 v[136:137], v[84:85], v[246:247] op_sel:[0,1] op_sel_hi:[1,1]
	v_pk_mul_f32 v[138:139], v[86:87], v[246:247] op_sel:[0,1] op_sel_hi:[1,1]
	v_pk_mul_f32 v[140:141], v[132:133], v[148:149]
	v_pk_mul_f32 v[142:143], v[134:135], v[148:149]
	v_pk_mul_f32 v[144:145], v[136:137], v[148:149]
	v_pk_mul_f32 v[146:147], v[138:139], v[148:149]
	v_exp_f32_e32 v140, v140
	v_exp_f32_e32 v141, v141
	v_exp_f32_e32 v142, v142
	v_exp_f32_e32 v143, v143
	v_exp_f32_e32 v144, v144
	v_exp_f32_e32 v145, v145
	v_exp_f32_e32 v146, v146
	v_exp_f32_e32 v147, v147
	v_pk_add_f32 v[140:141], v[140:141], v[150:151]
	v_pk_add_f32 v[142:143], v[142:143], v[150:151]
	v_pk_add_f32 v[144:145], v[144:145], v[150:151]
	v_pk_add_f32 v[146:147], v[146:147], v[150:151]
	v_rcp_f32_e32 v140, v140
	v_rcp_f32_e32 v141, v141
	v_rcp_f32_e32 v142, v142
	v_rcp_f32_e32 v143, v143
	v_rcp_f32_e32 v144, v144
	v_rcp_f32_e32 v145, v145
	v_rcp_f32_e32 v146, v146
	v_rcp_f32_e32 v147, v147
	v_cvt_pk_bf16_f32 v132, v140, v141
	v_cvt_pk_bf16_f32 v133, v142, v143
	v_cvt_pk_bf16_f32 v134, v144, v145
	v_cvt_pk_bf16_f32 v135, v146, v147
	global_store_dwordx4 v152, v[132:135], s[4:5] offset:512
	s_add_u32 s4, s4, 0x8000
	s_addc_u32 s5, s5, 0
	v_pk_mul_f32 v[132:133], v[80:81], v[248:249] op_sel_hi:[1,0]
	v_pk_mul_f32 v[134:135], v[82:83], v[248:249] op_sel_hi:[1,0]
	v_pk_mul_f32 v[136:137], v[76:77], v[248:249] op_sel_hi:[1,0]
	v_pk_mul_f32 v[138:139], v[78:79], v[248:249] op_sel_hi:[1,0]
	v_pk_mul_f32 v[140:141], v[132:133], v[148:149]
	v_pk_mul_f32 v[142:143], v[134:135], v[148:149]
	v_pk_mul_f32 v[144:145], v[136:137], v[148:149]
	v_pk_mul_f32 v[146:147], v[138:139], v[148:149]
	v_exp_f32_e32 v140, v140
	v_exp_f32_e32 v141, v141
	v_exp_f32_e32 v142, v142
	v_exp_f32_e32 v143, v143
	v_exp_f32_e32 v144, v144
	v_exp_f32_e32 v145, v145
	v_exp_f32_e32 v146, v146
	v_exp_f32_e32 v147, v147
	v_pk_add_f32 v[140:141], v[140:141], v[150:151]
	v_pk_add_f32 v[142:143], v[142:143], v[150:151]
	v_pk_add_f32 v[144:145], v[144:145], v[150:151]
	v_pk_add_f32 v[146:147], v[146:147], v[150:151]
	v_rcp_f32_e32 v140, v140
	v_rcp_f32_e32 v141, v141
	v_rcp_f32_e32 v142, v142
	v_rcp_f32_e32 v143, v143
	v_rcp_f32_e32 v144, v144
	v_rcp_f32_e32 v145, v145
	v_rcp_f32_e32 v146, v146
	v_rcp_f32_e32 v147, v147
	v_cvt_pk_bf16_f32 v132, v140, v141
	v_cvt_pk_bf16_f32 v133, v142, v143
	v_cvt_pk_bf16_f32 v134, v144, v145
	v_cvt_pk_bf16_f32 v135, v146, v147
	global_store_dwordx4 v152, v[132:135], s[4:5] offset:512
	s_add_u32 s4, s4, 0x8000
	s_addc_u32 s5, s5, 0
	v_pk_mul_f32 v[132:133], v[72:73], v[248:249] op_sel:[0,1] op_sel_hi:[1,1]
	v_pk_mul_f32 v[134:135], v[74:75], v[248:249] op_sel:[0,1] op_sel_hi:[1,1]
	v_pk_mul_f32 v[136:137], v[68:69], v[248:249] op_sel:[0,1] op_sel_hi:[1,1]
	v_pk_mul_f32 v[138:139], v[70:71], v[248:249] op_sel:[0,1] op_sel_hi:[1,1]
	v_pk_mul_f32 v[140:141], v[132:133], v[148:149]
	v_pk_mul_f32 v[142:143], v[134:135], v[148:149]
	v_pk_mul_f32 v[144:145], v[136:137], v[148:149]
	v_pk_mul_f32 v[146:147], v[138:139], v[148:149]
	v_exp_f32_e32 v140, v140
	v_exp_f32_e32 v141, v141
	v_exp_f32_e32 v142, v142
	v_exp_f32_e32 v143, v143
	v_exp_f32_e32 v144, v144
	v_exp_f32_e32 v145, v145
	v_exp_f32_e32 v146, v146
	v_exp_f32_e32 v147, v147
	v_pk_add_f32 v[140:141], v[140:141], v[150:151]
	v_pk_add_f32 v[142:143], v[142:143], v[150:151]
	v_pk_add_f32 v[144:145], v[144:145], v[150:151]
	v_pk_add_f32 v[146:147], v[146:147], v[150:151]
	v_rcp_f32_e32 v140, v140
	v_rcp_f32_e32 v141, v141
	v_rcp_f32_e32 v142, v142
	v_rcp_f32_e32 v143, v143
	v_rcp_f32_e32 v144, v144
	v_rcp_f32_e32 v145, v145
	v_rcp_f32_e32 v146, v146
	v_rcp_f32_e32 v147, v147
	v_cvt_pk_bf16_f32 v132, v140, v141
	v_cvt_pk_bf16_f32 v133, v142, v143
	v_cvt_pk_bf16_f32 v134, v144, v145
	v_cvt_pk_bf16_f32 v135, v146, v147
	global_store_dwordx4 v152, v[132:135], s[4:5] offset:512
.Lsig_a_done:
.LBB0_70:
	s_mov_b64 s[0:1], 0
.LBB0_71:
	s_andn2_b64 vcc, exec, s[0:1]
	s_cbranch_vccnz .LBB0_74
	s_lshl_b32 s0, s48, 8
	s_add_i32 s0, s0, s31
	v_or_b32_e32 v134, s0, v181
	v_ashrrev_i32_e32 v135, 31, v134
	v_lshl_add_u64 v[142:143], v[134:135], 2, s[70:71]
	v_mov_b32_e32 v144, v164
	v_mov_b32_e32 v146, v165
	v_mov_b32_e32 v138, v166
	v_mov_b32_e32 v136, v167
	s_or_b32 s1, s74, s49
	v_or_b32_e32 v2, s1, v242
	s_add_i32 s3, s1, 0xfffff180
	s_add_i32 s4, s0, 0xffffc000
	v_bitop3_b32 v140, s1, 56, v242 bitop3:0xc8
	s_ashr_i32 s1, s3, 6
	v_add_u32_e32 v2, 0xfffff184, v2
	s_ashr_i32 s3, s0, 11
	v_bitop3_b32 v135, s0, v250, v181 bitop3:0xc8
	s_lshr_b32 s4, s4, 4
	v_ashrrev_i32_e32 v139, 6, v2
	v_add_u32_e32 v2, 0x80, v135
	v_mov_b32_e32 v135, s3
	v_mov_b32_e32 v145, s4
	v_cmp_gt_i32_e32 vcc, s20, v134
	v_mov_b64_e32 v[132:133], s[92:93]
	v_or_b32_e32 v137, 4, v140
	v_cndmask_b32_e32 v142, v145, v135, vcc
	v_lshlrev_b32_e32 v143, 1, v142
	v_add_u32_e32 v142, s1, v143
	v_add_u32_e32 v148, v143, v139
	v_ashrrev_i32_e32 v143, 31, v142
	v_lshlrev_b64 v[142:143], 6, v[142:143]
	v_or_b32_e32 v142, v142, v140
	v_cndmask_b32_e32 v2, v244, v2, vcc
	v_ashrrev_i32_e32 v149, 31, v148
	v_mad_u64_u32 v[150:151], s[4:5], v142, s89, v[132:133]
	v_lshlrev_b32_e32 v2, 1, v2
	v_lshlrev_b64 v[148:149], 6, v[148:149]
	v_mad_i32_i24 v151, v143, s89, v151
	v_or_b32_e32 v145, v148, v137
	v_lshl_add_u64 v[142:143], v[150:151], 0, v[2:3]
	s_movk_i32 s17, 0x1000
	v_mad_u64_u32 v[152:153], s[4:5], v145, s89, v[132:133]
	v_add_co_u32_e32 v150, vcc, s17, v142
	v_mad_i32_i24 v153, v149, s89, v153
	s_nop 0
	v_addc_co_u32_e32 v151, vcc, 0, v143, vcc
	s_movk_i32 s16, 0x2000
	v_lshl_add_u64 v[148:149], v[152:153], 0, v[2:3]
	v_add_co_u32_e32 v152, vcc, s16, v142
	s_movk_i32 s21, 0x3000
	s_nop 0
	v_addc_co_u32_e32 v153, vcc, 0, v143, vcc
	v_add_co_u32_e32 v154, vcc, s21, v142
	s_movk_i32 s3, 0x7df
	s_nop 0
	v_addc_co_u32_e32 v155, vcc, 0, v143, vcc
	v_add_co_u32_e32 v156, vcc, s17, v148
	v_or_b32_e32 v141, 16, v134
	s_nop 0
	v_addc_co_u32_e32 v157, vcc, 0, v149, vcc
	v_add_co_u32_e32 v158, vcc, s16, v148
	v_or_b32_e32 v188, 32, v134
	s_nop 0
	v_addc_co_u32_e32 v159, vcc, 0, v149, vcc
	v_or_b32_e32 v189, 48, v134
	v_pk_mul_f32 v[162:163], v[128:129], v[144:145] op_sel_hi:[1,0]
	v_pk_mul_f32 v[160:161], v[130:131], v[144:145] op_sel_hi:[1,0]
	v_pk_mul_f32 v[168:169], v[126:127], v[144:145] op_sel_hi:[1,0]
	v_pk_mul_f32 v[144:145], v[124:125], v[144:145] op_sel_hi:[1,0]
	v_cvt_pk_bf16_f32 v2, v162, s0
	v_cvt_pk_bf16_f32 v147, v163, s0
	v_cvt_pk_bf16_f32 v160, v160, s0
	v_cvt_pk_bf16_f32 v161, v161, s0
	v_cvt_pk_bf16_f32 v144, v144, s0
	v_cvt_pk_bf16_f32 v145, v145, s0
	v_cvt_pk_bf16_f32 v162, v168, s0
	global_store_short v[142:143], v2, off
	global_store_short v[150:151], v147, off offset:256
	global_store_short v[152:153], v160, off offset:512
	global_store_short v[154:155], v161, off offset:768
	global_store_short v[148:149], v144, off
	global_store_short v[156:157], v145, off offset:256
	global_store_short v[158:159], v162, off offset:512
	v_add_co_u32_e32 v142, vcc, s21, v148
	v_bitop3_b32 v2, v134, s3, 16 bitop3:0xc8
	s_add_i32 s3, s0, 0xffffc010
	v_cvt_pk_bf16_f32 v163, v169, s0
	v_addc_co_u32_e32 v143, vcc, 0, v149, vcc
	s_lshr_b32 s3, s3, 4
	global_store_short v[142:143], v163, off offset:768
	v_pk_mul_f32 v[142:143], v[122:123], v[146:147] op_sel_hi:[1,0]
	v_pk_mul_f32 v[144:145], v[120:121], v[146:147] op_sel_hi:[1,0]
	v_mov_b32_e32 v147, s3
	v_cmp_gt_i32_e32 vcc, s20, v141
	v_add_u32_e32 v2, 0x80, v2
	v_cvt_pk_bf16_f32 v144, v144, s0
	v_cndmask_b32_e32 v141, v147, v135, vcc
	v_lshlrev_b32_e32 v141, 1, v141
	v_add_u32_e32 v148, s1, v141
	v_ashrrev_i32_e32 v149, 31, v148
	v_lshlrev_b64 v[148:149], 6, v[148:149]
	v_or_b32_e32 v147, v148, v140
	v_cndmask_b32_e32 v2, v244, v2, vcc
	v_mad_u64_u32 v[150:151], s[4:5], v147, s89, v[132:133]
	v_mad_i32_i24 v151, v149, s89, v151
	v_lshlrev_b32_e32 v2, 1, v2
	v_lshl_add_u64 v[148:149], v[150:151], 0, v[2:3]
	global_store_short v[148:149], v144, off
	v_add_co_u32_e32 v144, vcc, s17, v148
	v_cvt_pk_bf16_f32 v147, v145, s0
	s_nop 0
	v_addc_co_u32_e32 v145, vcc, 0, v149, vcc
	global_store_short v[144:145], v147, off offset:256
	v_add_co_u32_e32 v144, vcc, s16, v148
	v_cvt_pk_bf16_f32 v142, v142, s0
	s_nop 0
	v_addc_co_u32_e32 v145, vcc, 0, v149, vcc
	global_store_short v[144:145], v142, off offset:512
	v_add_co_u32_e32 v142, vcc, s21, v148
	v_cvt_pk_bf16_f32 v144, v143, s0
	s_nop 0
	v_addc_co_u32_e32 v143, vcc, 0, v149, vcc
	global_store_short v[142:143], v144, off offset:768
	v_pk_mul_f32 v[142:143], v[118:119], v[146:147] op_sel_hi:[1,0]
	v_pk_mul_f32 v[144:145], v[116:117], v[146:147] op_sel_hi:[1,0]
	v_add_u32_e32 v146, v141, v139
	v_ashrrev_i32_e32 v147, 31, v146
	v_lshlrev_b64 v[146:147], 6, v[146:147]
	v_or_b32_e32 v141, v146, v137
	v_mad_u64_u32 v[148:149], s[4:5], v141, s89, v[132:133]
	v_mad_i32_i24 v149, v147, s89, v149
	v_lshl_add_u64 v[146:147], v[148:149], 0, v[2:3]
	v_cvt_pk_bf16_f32 v2, v144, s0
	v_add_co_u32_e32 v144, vcc, s17, v146
	global_store_short v[146:147], v2, off
	v_cvt_pk_bf16_f32 v2, v145, s0
	v_addc_co_u32_e32 v145, vcc, 0, v147, vcc
	global_store_short v[144:145], v2, off offset:256
	v_add_co_u32_e32 v144, vcc, s16, v146
	v_cvt_pk_bf16_f32 v2, v142, s0
	s_nop 0
	v_addc_co_u32_e32 v145, vcc, 0, v147, vcc
	v_add_co_u32_e32 v142, vcc, s21, v146
	global_store_short v[144:145], v2, off offset:512
	v_cvt_pk_bf16_f32 v2, v143, s0
	v_addc_co_u32_e32 v143, vcc, 0, v147, vcc
	s_movk_i32 s3, 0x7ef
	global_store_short v[142:143], v2, off offset:768
	v_bitop3_b32 v2, v134, s3, 32 bitop3:0xc8
	s_add_i32 s3, s0, 0xffffc020
	s_lshr_b32 s3, s3, 4
	v_mov_b32_e32 v141, s3
	v_cmp_gt_i32_e32 vcc, s20, v188
	v_add_u32_e32 v2, 0x80, v2
	v_pk_mul_f32 v[144:145], v[112:113], v[138:139] op_sel_hi:[1,0]
	v_cndmask_b32_e32 v141, v141, v135, vcc
	v_lshlrev_b32_e32 v141, 1, v141
	v_add_u32_e32 v146, s1, v141
	v_ashrrev_i32_e32 v147, 31, v146
	v_lshlrev_b64 v[146:147], 6, v[146:147]
	v_or_b32_e32 v146, v146, v140
	v_cndmask_b32_e32 v2, v244, v2, vcc
	v_mad_u64_u32 v[148:149], s[4:5], v146, s89, v[132:133]
	v_mad_i32_i24 v149, v147, s89, v149
	v_lshlrev_b32_e32 v2, 1, v2
	v_lshl_add_u64 v[146:147], v[148:149], 0, v[2:3]
	v_cvt_pk_bf16_f32 v144, v144, s0
	global_store_short v[146:147], v144, off
	v_add_co_u32_e32 v144, vcc, s17, v146
	v_cvt_pk_bf16_f32 v148, v145, s0
	s_nop 0
	v_addc_co_u32_e32 v145, vcc, 0, v147, vcc
	v_pk_mul_f32 v[142:143], v[114:115], v[138:139] op_sel_hi:[1,0]
	global_store_short v[144:145], v148, off offset:256
	v_add_co_u32_e32 v144, vcc, s16, v146
	v_cvt_pk_bf16_f32 v142, v142, s0
	s_nop 0
	v_addc_co_u32_e32 v145, vcc, 0, v147, vcc
	global_store_short v[144:145], v142, off offset:512
	v_add_co_u32_e32 v142, vcc, s21, v146
	v_add_u32_e32 v146, v141, v139
	v_cvt_pk_bf16_f32 v144, v143, s0
	v_addc_co_u32_e32 v143, vcc, 0, v147, vcc
	v_ashrrev_i32_e32 v147, 31, v146
	v_lshlrev_b64 v[146:147], 6, v[146:147]
	global_store_short v[142:143], v144, off offset:768
	v_pk_mul_f32 v[142:143], v[110:111], v[138:139] op_sel_hi:[1,0]
	v_pk_mul_f32 v[144:145], v[108:109], v[138:139] op_sel_hi:[1,0]
	v_or_b32_e32 v138, v146, v137
	v_mad_u64_u32 v[148:149], s[4:5], v138, s89, v[132:133]
	v_mad_i32_i24 v149, v147, s89, v149
	v_lshl_add_u64 v[146:147], v[148:149], 0, v[2:3]
	v_cvt_pk_bf16_f32 v2, v144, s0
	v_add_co_u32_e32 v144, vcc, s17, v146
	global_store_short v[146:147], v2, off
	v_cvt_pk_bf16_f32 v2, v145, s0
	v_addc_co_u32_e32 v145, vcc, 0, v147, vcc
	global_store_short v[144:145], v2, off offset:256
	v_add_co_u32_e32 v144, vcc, s16, v146
	v_cvt_pk_bf16_f32 v2, v142, s0
	s_nop 0
	v_addc_co_u32_e32 v145, vcc, 0, v147, vcc
	v_add_co_u32_e32 v142, vcc, s21, v146
	global_store_short v[144:145], v2, off offset:512
	v_cvt_pk_bf16_f32 v2, v143, s0
	v_addc_co_u32_e32 v143, vcc, 0, v147, vcc
	s_movk_i32 s3, 0x7ff
	global_store_short v[142:143], v2, off offset:768
	v_bitop3_b32 v2, v134, s3, 48 bitop3:0xc8
	s_add_i32 s3, s0, 0xffffc030
	s_lshr_b32 s3, s3, 4
	v_mov_b32_e32 v134, s3
	v_cmp_gt_i32_e32 vcc, s20, v189
	v_add_u32_e32 v2, 0x80, v2
	v_pk_mul_f32 v[144:145], v[104:105], v[136:137] op_sel_hi:[1,0]
	v_cndmask_b32_e32 v134, v134, v135, vcc
	v_lshlrev_b32_e32 v138, 1, v134
	v_add_u32_e32 v134, s1, v138
	v_ashrrev_i32_e32 v135, 31, v134
	v_lshlrev_b64 v[134:135], 6, v[134:135]
	v_or_b32_e32 v134, v134, v140
	v_cndmask_b32_e32 v2, v244, v2, vcc
	v_mad_u64_u32 v[146:147], s[4:5], v134, s89, v[132:133]
	v_mad_i32_i24 v147, v135, s89, v147
	v_lshlrev_b32_e32 v2, 1, v2
	v_lshl_add_u64 v[134:135], v[146:147], 0, v[2:3]
	v_cvt_pk_bf16_f32 v141, v144, s0
	v_add_co_u32_e32 v144, vcc, s17, v134
	global_store_short v[134:135], v141, off
	v_cvt_pk_bf16_f32 v141, v145, s0
	v_addc_co_u32_e32 v145, vcc, 0, v135, vcc
	v_pk_mul_f32 v[142:143], v[106:107], v[136:137] op_sel_hi:[1,0]
	global_store_short v[144:145], v141, off offset:256
	v_add_co_u32_e32 v144, vcc, s16, v134
	v_cvt_pk_bf16_f32 v141, v142, s0
	s_nop 0
	v_addc_co_u32_e32 v145, vcc, 0, v135, vcc
	global_store_short v[144:145], v141, off offset:512
	v_add_u32_e32 v144, v138, v139
	v_add_co_u32_e32 v134, vcc, s21, v134
	v_ashrrev_i32_e32 v145, 31, v144
	v_cvt_pk_bf16_f32 v141, v143, s0
	v_addc_co_u32_e32 v135, vcc, 0, v135, vcc
	v_lshlrev_b64 v[144:145], 6, v[144:145]
	global_store_short v[134:135], v141, off offset:768
	v_pk_mul_f32 v[134:135], v[102:103], v[136:137] op_sel_hi:[1,0]
	v_pk_mul_f32 v[142:143], v[100:101], v[136:137] op_sel_hi:[1,0]
	v_or_b32_e32 v136, v144, v137
	v_mad_u64_u32 v[132:133], s[4:5], v136, s89, v[132:133]
	v_mad_i32_i24 v133, v145, s89, v133
	v_lshl_add_u64 v[132:133], v[132:133], 0, v[2:3]
	v_cvt_pk_bf16_f32 v2, v142, s0
	v_add_co_u32_e32 v142, vcc, 0x1000, v132
	global_store_short v[132:133], v2, off
	v_cvt_pk_bf16_f32 v2, v143, s0
	v_addc_co_u32_e32 v143, vcc, 0, v133, vcc
	global_store_short v[142:143], v2, off offset:256
	v_add_co_u32_e32 v142, vcc, 0x2000, v132
	v_cvt_pk_bf16_f32 v2, v134, s0
	s_nop 0
	v_addc_co_u32_e32 v143, vcc, 0, v133, vcc
	v_add_co_u32_e32 v132, vcc, 0x3000, v132
	global_store_short v[142:143], v2, off offset:512
	v_cvt_pk_bf16_f32 v2, v135, s0
	v_addc_co_u32_e32 v133, vcc, 0, v133, vcc
	s_cmp_eq_u32 s48, 64
	global_store_short v[132:133], v2, off offset:768
	s_cbranch_scc1 .LBB0_74
	s_add_i32 s3, s0, 0x80
	v_or_b32_e32 v134, s3, v181
	v_ashrrev_i32_e32 v135, 31, v134
	v_lshl_add_u64 v[142:143], v[134:135], 2, s[70:71]
	v_mov_b32_e32 v138, v246
	v_mov_b32_e32 v144, v247
	s_add_i32 s4, s0, 0xffffc080
	s_ashr_i32 s5, s3, 11
	v_bitop3_b32 v2, s3, v250, v181 bitop3:0xc8
	s_lshr_b32 s3, s4, 4
	v_mov_b32_e32 v136, s3
	v_mov_b32_e32 v197, s5
	v_cmp_gt_i32_e32 vcc, s20, v134
	v_mov_b64_e32 v[132:133], s[92:93]
	v_add_u32_e32 v2, 0x80, v2
	v_cndmask_b32_e32 v147, v136, v197, vcc
	v_mov_b32_e32 v146, v248
	v_mov_b32_e32 v136, v249
	v_lshlrev_b32_e32 v143, 1, v147
	v_add_u32_e32 v142, s1, v143
	v_add_u32_e32 v148, v143, v139
	v_ashrrev_i32_e32 v143, 31, v142
	v_lshlrev_b64 v[142:143], 6, v[142:143]
	v_or_b32_e32 v142, v142, v140
	v_cndmask_b32_e32 v2, v244, v2, vcc
	v_ashrrev_i32_e32 v149, 31, v148
	v_mad_u64_u32 v[150:151], s[4:5], v142, s89, v[132:133]
	v_lshlrev_b32_e32 v2, 1, v2
	v_lshlrev_b64 v[148:149], 6, v[148:149]
	v_mad_i32_i24 v151, v143, s89, v151
	v_or_b32_e32 v147, v148, v137
	v_lshl_add_u64 v[142:143], v[150:151], 0, v[2:3]
	v_mad_u64_u32 v[152:153], s[4:5], v147, s89, v[132:133]
	v_add_co_u32_e32 v150, vcc, s17, v142
	v_mad_i32_i24 v153, v149, s89, v153
	s_nop 0
	v_addc_co_u32_e32 v151, vcc, 0, v143, vcc
	v_lshl_add_u64 v[148:149], v[152:153], 0, v[2:3]
	v_add_co_u32_e32 v152, vcc, s16, v142
	s_movk_i32 s3, 0x7df
	s_nop 0
	v_addc_co_u32_e32 v153, vcc, 0, v143, vcc
	v_add_co_u32_e32 v154, vcc, s21, v142
	v_bitop3_b32 v145, v134, s3, 16 bitop3:0xc8
	s_nop 0
	v_addc_co_u32_e32 v155, vcc, 0, v143, vcc
	v_add_co_u32_e32 v156, vcc, s17, v148
	s_add_i32 s3, s0, 0xffffc090
	s_nop 0
	v_addc_co_u32_e32 v157, vcc, 0, v149, vcc
	v_add_co_u32_e32 v158, vcc, s16, v148
	v_or_b32_e32 v135, 16, v134
	s_nop 0
	v_addc_co_u32_e32 v159, vcc, 0, v149, vcc
	v_add_co_u32_e32 v160, vcc, s21, v148
	s_lshr_b32 s3, s3, 4
	s_nop 0
	v_addc_co_u32_e32 v161, vcc, 0, v149, vcc
	v_cmp_gt_i32_e32 vcc, s20, v135
	v_or_b32_e32 v141, 32, v134
	v_or_b32_e32 v196, 48, v134
	v_pk_mul_f32 v[168:169], v[96:97], v[138:139] op_sel_hi:[1,0]
	v_pk_mul_f32 v[162:163], v[98:99], v[138:139] op_sel_hi:[1,0]
	v_pk_mul_f32 v[188:189], v[94:95], v[138:139] op_sel_hi:[1,0]
	v_pk_mul_f32 v[190:191], v[92:93], v[138:139] op_sel_hi:[1,0]
	v_cvt_pk_bf16_f32 v2, v168, s0
	v_cvt_pk_bf16_f32 v138, v169, s0
	v_cvt_pk_bf16_f32 v147, v162, s0
	v_cvt_pk_bf16_f32 v162, v163, s0
	v_cvt_pk_bf16_f32 v163, v190, s0
	v_cvt_pk_bf16_f32 v168, v191, s0
	v_cvt_pk_bf16_f32 v169, v188, s0
	v_cvt_pk_bf16_f32 v188, v189, s0
	global_store_short v[142:143], v2, off
	global_store_short v[150:151], v138, off offset:256
	global_store_short v[152:153], v147, off offset:512
	global_store_short v[154:155], v162, off offset:768
	global_store_short v[148:149], v163, off
	global_store_short v[156:157], v168, off offset:256
	global_store_short v[158:159], v169, off offset:512
	global_store_short v[160:161], v188, off offset:768
	v_mov_b32_e32 v138, s3
	v_cndmask_b32_e32 v135, v138, v197, vcc
	v_lshlrev_b32_e32 v135, 1, v135
	v_add_u32_e32 v142, s1, v135
	v_ashrrev_i32_e32 v143, 31, v142
	v_lshlrev_b64 v[142:143], 6, v[142:143]
	v_add_u32_e32 v2, 0x80, v145
	v_or_b32_e32 v138, v142, v140
	v_cndmask_b32_e32 v2, v244, v2, vcc
	v_mad_u64_u32 v[148:149], s[4:5], v138, s89, v[132:133]
	v_mad_i32_i24 v149, v143, s89, v149
	v_lshlrev_b32_e32 v2, 1, v2
	v_pk_mul_f32 v[194:195], v[88:89], v[144:145] op_sel_hi:[1,0]
	v_lshl_add_u64 v[142:143], v[148:149], 0, v[2:3]
	v_cvt_pk_bf16_f32 v138, v194, s0
	v_add_co_u32_e32 v148, vcc, s17, v142
	global_store_short v[142:143], v138, off
	v_cvt_pk_bf16_f32 v138, v195, s0
	v_addc_co_u32_e32 v149, vcc, 0, v143, vcc
	v_pk_mul_f32 v[192:193], v[90:91], v[144:145] op_sel_hi:[1,0]
	global_store_short v[148:149], v138, off offset:256
	v_add_co_u32_e32 v148, vcc, s16, v142
	v_cvt_pk_bf16_f32 v138, v192, s0
	s_nop 0
	v_addc_co_u32_e32 v149, vcc, 0, v143, vcc
	global_store_short v[148:149], v138, off offset:512
	v_add_u32_e32 v148, v135, v139
	v_ashrrev_i32_e32 v149, 31, v148
	v_lshlrev_b64 v[148:149], 6, v[148:149]
	v_or_b32_e32 v135, v148, v137
	v_add_co_u32_e32 v142, vcc, s21, v142
	v_mad_u64_u32 v[150:151], s[4:5], v135, s89, v[132:133]
	v_cvt_pk_bf16_f32 v138, v193, s0
	v_addc_co_u32_e32 v143, vcc, 0, v143, vcc
	v_mad_i32_i24 v151, v149, s89, v151
	global_store_short v[142:143], v138, off offset:768
	v_pk_mul_f32 v[142:143], v[86:87], v[144:145] op_sel_hi:[1,0]
	v_pk_mul_f32 v[144:145], v[84:85], v[144:145] op_sel_hi:[1,0]
	v_lshl_add_u64 v[148:149], v[150:151], 0, v[2:3]
	v_cvt_pk_bf16_f32 v2, v144, s0
	v_add_co_u32_e32 v144, vcc, s17, v148
	global_store_short v[148:149], v2, off
	v_cvt_pk_bf16_f32 v2, v145, s0
	v_addc_co_u32_e32 v145, vcc, 0, v149, vcc
	global_store_short v[144:145], v2, off offset:256
	v_add_co_u32_e32 v144, vcc, s16, v148
	v_cvt_pk_bf16_f32 v2, v142, s0
	s_nop 0
	v_addc_co_u32_e32 v145, vcc, 0, v149, vcc
	v_add_co_u32_e32 v142, vcc, s21, v148
	global_store_short v[144:145], v2, off offset:512
	v_cvt_pk_bf16_f32 v2, v143, s0
	v_addc_co_u32_e32 v143, vcc, 0, v149, vcc
	s_movk_i32 s3, 0x7ef
	global_store_short v[142:143], v2, off offset:768
	v_bitop3_b32 v2, v134, s3, 32 bitop3:0xc8
	s_add_i32 s3, s0, 0xffffc0a0
	s_lshr_b32 s3, s3, 4
	v_mov_b32_e32 v135, s3
	v_cmp_gt_i32_e32 vcc, s20, v141
	v_add_u32_e32 v2, 0x80, v2
	v_pk_mul_f32 v[144:145], v[80:81], v[146:147] op_sel_hi:[1,0]
	v_cndmask_b32_e32 v135, v135, v197, vcc
	v_lshlrev_b32_e32 v135, 1, v135
	v_add_u32_e32 v148, s1, v135
	v_ashrrev_i32_e32 v149, 31, v148
	v_lshlrev_b64 v[148:149], 6, v[148:149]
	v_or_b32_e32 v138, v148, v140
	v_cndmask_b32_e32 v2, v244, v2, vcc
	v_mad_u64_u32 v[150:151], s[4:5], v138, s89, v[132:133]
	v_mad_i32_i24 v151, v149, s89, v151
	v_lshlrev_b32_e32 v2, 1, v2
	v_lshl_add_u64 v[148:149], v[150:151], 0, v[2:3]
	v_cvt_pk_bf16_f32 v138, v144, s0
	v_add_co_u32_e32 v144, vcc, s17, v148
	global_store_short v[148:149], v138, off
	v_cvt_pk_bf16_f32 v138, v145, s0
	v_addc_co_u32_e32 v145, vcc, 0, v149, vcc
	global_store_short v[144:145], v138, off offset:256
	v_add_co_u32_e32 v144, vcc, s16, v148
	v_pk_mul_f32 v[142:143], v[82:83], v[146:147] op_sel_hi:[1,0]
	s_nop 0
	v_addc_co_u32_e32 v145, vcc, 0, v149, vcc
	v_cvt_pk_bf16_f32 v138, v142, s0
	v_add_co_u32_e32 v142, vcc, s21, v148
	global_store_short v[144:145], v138, off offset:512
	v_cvt_pk_bf16_f32 v138, v143, s0
	v_addc_co_u32_e32 v143, vcc, 0, v149, vcc
	global_store_short v[142:143], v138, off offset:768
	v_pk_mul_f32 v[142:143], v[78:79], v[146:147] op_sel_hi:[1,0]
	v_pk_mul_f32 v[144:145], v[76:77], v[146:147] op_sel_hi:[1,0]
	v_add_u32_e32 v146, v135, v139
	v_ashrrev_i32_e32 v147, 31, v146
	v_lshlrev_b64 v[146:147], 6, v[146:147]
	v_or_b32_e32 v135, v146, v137
	v_mad_u64_u32 v[148:149], s[4:5], v135, s89, v[132:133]
	v_mad_i32_i24 v149, v147, s89, v149
	v_lshl_add_u64 v[146:147], v[148:149], 0, v[2:3]
	v_cvt_pk_bf16_f32 v2, v144, s0
	v_add_co_u32_e32 v144, vcc, s17, v146
	global_store_short v[146:147], v2, off
	v_cvt_pk_bf16_f32 v2, v145, s0
	v_addc_co_u32_e32 v145, vcc, 0, v147, vcc
	global_store_short v[144:145], v2, off offset:256
	v_add_co_u32_e32 v144, vcc, s16, v146
	v_cvt_pk_bf16_f32 v2, v142, s0
	s_nop 0
	v_addc_co_u32_e32 v145, vcc, 0, v147, vcc
	global_store_short v[144:145], v2, off offset:512
	v_cvt_pk_bf16_f32 v2, v143, s0
	v_add_co_u32_e32 v142, vcc, s21, v146
	s_addk_i32 s0, 0xc0b0
	s_nop 0
	v_addc_co_u32_e32 v143, vcc, 0, v147, vcc
	s_movk_i32 s3, 0x7ff
	s_lshr_b32 s0, s0, 4
	global_store_short v[142:143], v2, off offset:768
	v_bitop3_b32 v2, v134, s3, 48 bitop3:0xc8
	v_mov_b32_e32 v134, s0
	v_cmp_gt_i32_e32 vcc, s20, v196
	v_add_u32_e32 v2, 0x80, v2
	v_pk_mul_f32 v[144:145], v[72:73], v[136:137] op_sel_hi:[1,0]
	v_cndmask_b32_e32 v134, v134, v197, vcc
	v_lshlrev_b32_e32 v138, 1, v134
	v_add_u32_e32 v134, s1, v138
	v_ashrrev_i32_e32 v135, 31, v134
	v_lshlrev_b64 v[134:135], 6, v[134:135]
	v_or_b32_e32 v134, v134, v140
	v_cndmask_b32_e32 v2, v244, v2, vcc
	v_mad_u64_u32 v[140:141], s[0:1], v134, s89, v[132:133]
	v_mad_i32_i24 v141, v135, s89, v141
	v_lshlrev_b32_e32 v2, 1, v2
	v_lshl_add_u64 v[134:135], v[140:141], 0, v[2:3]
	v_cvt_pk_bf16_f32 v140, v144, s0
	global_store_short v[134:135], v140, off
	v_add_co_u32_e32 v140, vcc, s17, v134
	v_cvt_pk_bf16_f32 v144, v145, s0
	s_nop 0
	v_addc_co_u32_e32 v141, vcc, 0, v135, vcc
	global_store_short v[140:141], v144, off offset:256
	v_add_co_u32_e32 v140, vcc, s16, v134
	v_pk_mul_f32 v[142:143], v[74:75], v[136:137] op_sel_hi:[1,0]
	s_nop 0
	v_addc_co_u32_e32 v141, vcc, 0, v135, vcc
	v_add_u32_e32 v138, v138, v139
	v_cvt_pk_bf16_f32 v142, v142, s0
	v_add_co_u32_e32 v134, vcc, s21, v134
	v_ashrrev_i32_e32 v139, 31, v138
	global_store_short v[140:141], v142, off offset:512
	v_cvt_pk_bf16_f32 v140, v143, s0
	v_addc_co_u32_e32 v135, vcc, 0, v135, vcc
	v_lshlrev_b64 v[138:139], 6, v[138:139]
	global_store_short v[134:135], v140, off offset:768
	v_pk_mul_f32 v[134:135], v[70:71], v[136:137] op_sel_hi:[1,0]
	v_pk_mul_f32 v[140:141], v[68:69], v[136:137] op_sel_hi:[1,0]
	v_or_b32_e32 v136, v138, v137
	v_mad_u64_u32 v[132:133], s[0:1], v136, s89, v[132:133]
	v_mad_i32_i24 v133, v139, s89, v133
	v_lshl_add_u64 v[132:133], v[132:133], 0, v[2:3]
	v_cvt_pk_bf16_f32 v2, v140, s0
	v_add_co_u32_e32 v136, vcc, 0x1000, v132
	global_store_short v[132:133], v2, off
	v_cvt_pk_bf16_f32 v2, v141, s0
	v_addc_co_u32_e32 v137, vcc, 0, v133, vcc
	global_store_short v[136:137], v2, off offset:256
	v_add_co_u32_e32 v136, vcc, 0x2000, v132
	v_cvt_pk_bf16_f32 v2, v134, s0
	s_nop 0
	v_addc_co_u32_e32 v137, vcc, 0, v133, vcc
	v_add_co_u32_e32 v132, vcc, 0x3000, v132
	global_store_short v[136:137], v2, off offset:512
	v_cvt_pk_bf16_f32 v2, v135, s0
	v_addc_co_u32_e32 v133, vcc, 0, v133, vcc
	global_store_short v[132:133], v2, off offset:768

.Lsec78_b:
	s_mov_b32 s3, 0x9ce6000
	s_cmp_eq_u32 s17, 8
	s_cselect_b32 s3, 0xbd25800, s3
	s_lshl_b32 s2, s48, 8
	v_add_u32_e32 v88, s2, v241
	v_lshlrev_b32_e32 v88, 11, v88
	v_or_b32_e32 v68, s74, v178
	v_lshl_add_u32 v88, v68, 1, v88
	s_add_u32 s4, s94, s3
	s_addc_u32 s5, s95, 0
	v_mov_b32_e32 v84, 0xbfb8aa3b
	v_mov_b32_e32 v85, 0xbfb8aa3b
	v_mov_b32_e32 v86, 1.0
	v_mov_b32_e32 v87, 1.0
	v_pk_mul_f32 v[68:69], v[64:65], v[164:165] op_sel_hi:[1,0]
	v_pk_mul_f32 v[70:71], v[66:67], v[164:165] op_sel_hi:[1,0]
	v_pk_mul_f32 v[72:73], v[60:61], v[164:165] op_sel_hi:[1,0]
	v_pk_mul_f32 v[74:75], v[62:63], v[164:165] op_sel_hi:[1,0]
	v_pk_mul_f32 v[76:77], v[68:69], v[84:85]
	v_pk_mul_f32 v[78:79], v[70:71], v[84:85]
	v_pk_mul_f32 v[80:81], v[72:73], v[84:85]
	v_pk_mul_f32 v[82:83], v[74:75], v[84:85]
	v_exp_f32_e32 v76, v76
	v_exp_f32_e32 v77, v77
	v_exp_f32_e32 v78, v78
	v_exp_f32_e32 v79, v79
	v_exp_f32_e32 v80, v80
	v_exp_f32_e32 v81, v81
	v_exp_f32_e32 v82, v82
	v_exp_f32_e32 v83, v83
	v_pk_add_f32 v[76:77], v[76:77], v[86:87]
	v_pk_add_f32 v[78:79], v[78:79], v[86:87]
	v_pk_add_f32 v[80:81], v[80:81], v[86:87]
	v_pk_add_f32 v[82:83], v[82:83], v[86:87]
	v_rcp_f32_e32 v76, v76
	v_rcp_f32_e32 v77, v77
	v_rcp_f32_e32 v78, v78
	v_rcp_f32_e32 v79, v79
	v_rcp_f32_e32 v80, v80
	v_rcp_f32_e32 v81, v81
	v_rcp_f32_e32 v82, v82
	v_rcp_f32_e32 v83, v83
	v_cvt_pk_bf16_f32 v68, v76, v77
	v_cvt_pk_bf16_f32 v69, v78, v79
	v_cvt_pk_bf16_f32 v70, v80, v81
	v_cvt_pk_bf16_f32 v71, v82, v83
	global_store_dwordx4 v88, v[68:71], s[4:5] offset:768
	s_add_u32 s4, s4, 0x8000
	s_addc_u32 s5, s5, 0
	v_pk_mul_f32 v[68:69], v[56:57], v[164:165] op_sel:[0,1] op_sel_hi:[1,1]
	v_pk_mul_f32 v[70:71], v[58:59], v[164:165] op_sel:[0,1] op_sel_hi:[1,1]
	v_pk_mul_f32 v[72:73], v[52:53], v[164:165] op_sel:[0,1] op_sel_hi:[1,1]
	v_pk_mul_f32 v[74:75], v[54:55], v[164:165] op_sel:[0,1] op_sel_hi:[1,1]
	v_pk_mul_f32 v[76:77], v[68:69], v[84:85]
	v_pk_mul_f32 v[78:79], v[70:71], v[84:85]
	v_pk_mul_f32 v[80:81], v[72:73], v[84:85]
	v_pk_mul_f32 v[82:83], v[74:75], v[84:85]
	v_exp_f32_e32 v76, v76
	v_exp_f32_e32 v77, v77
	v_exp_f32_e32 v78, v78
	v_exp_f32_e32 v79, v79
	v_exp_f32_e32 v80, v80
	v_exp_f32_e32 v81, v81
	v_exp_f32_e32 v82, v82
	v_exp_f32_e32 v83, v83
	v_pk_add_f32 v[76:77], v[76:77], v[86:87]
	v_pk_add_f32 v[78:79], v[78:79], v[86:87]
	v_pk_add_f32 v[80:81], v[80:81], v[86:87]
	v_pk_add_f32 v[82:83], v[82:83], v[86:87]
	v_rcp_f32_e32 v76, v76
	v_rcp_f32_e32 v77, v77
	v_rcp_f32_e32 v78, v78
	v_rcp_f32_e32 v79, v79
	v_rcp_f32_e32 v80, v80
	v_rcp_f32_e32 v81, v81
	v_rcp_f32_e32 v82, v82
	v_rcp_f32_e32 v83, v83
	v_cvt_pk_bf16_f32 v68, v76, v77
	v_cvt_pk_bf16_f32 v69, v78, v79
	v_cvt_pk_bf16_f32 v70, v80, v81
	v_cvt_pk_bf16_f32 v71, v82, v83
	global_store_dwordx4 v88, v[68:71], s[4:5] offset:768
	s_add_u32 s4, s4, 0x8000
	s_addc_u32 s5, s5, 0
	v_pk_mul_f32 v[68:69], v[48:49], v[166:167] op_sel_hi:[1,0]
	v_pk_mul_f32 v[70:71], v[50:51], v[166:167] op_sel_hi:[1,0]
	v_pk_mul_f32 v[72:73], v[44:45], v[166:167] op_sel_hi:[1,0]
	v_pk_mul_f32 v[74:75], v[46:47], v[166:167] op_sel_hi:[1,0]
	v_pk_mul_f32 v[76:77], v[68:69], v[84:85]
	v_pk_mul_f32 v[78:79], v[70:71], v[84:85]
	v_pk_mul_f32 v[80:81], v[72:73], v[84:85]
	v_pk_mul_f32 v[82:83], v[74:75], v[84:85]
	v_exp_f32_e32 v76, v76
	v_exp_f32_e32 v77, v77
	v_exp_f32_e32 v78, v78
	v_exp_f32_e32 v79, v79
	v_exp_f32_e32 v80, v80
	v_exp_f32_e32 v81, v81
	v_exp_f32_e32 v82, v82
	v_exp_f32_e32 v83, v83
	v_pk_add_f32 v[76:77], v[76:77], v[86:87]
	v_pk_add_f32 v[78:79], v[78:79], v[86:87]
	v_pk_add_f32 v[80:81], v[80:81], v[86:87]
	v_pk_add_f32 v[82:83], v[82:83], v[86:87]
	v_rcp_f32_e32 v76, v76
	v_rcp_f32_e32 v77, v77
	v_rcp_f32_e32 v78, v78
	v_rcp_f32_e32 v79, v79
	v_rcp_f32_e32 v80, v80
	v_rcp_f32_e32 v81, v81
	v_rcp_f32_e32 v82, v82
	v_rcp_f32_e32 v83, v83
	v_cvt_pk_bf16_f32 v68, v76, v77
	v_cvt_pk_bf16_f32 v69, v78, v79
	v_cvt_pk_bf16_f32 v70, v80, v81
	v_cvt_pk_bf16_f32 v71, v82, v83
	global_store_dwordx4 v88, v[68:71], s[4:5] offset:768
	s_add_u32 s4, s4, 0x8000
	s_addc_u32 s5, s5, 0
	v_pk_mul_f32 v[68:69], v[40:41], v[166:167] op_sel:[0,1] op_sel_hi:[1,1]
	v_pk_mul_f32 v[70:71], v[42:43], v[166:167] op_sel:[0,1] op_sel_hi:[1,1]
	v_pk_mul_f32 v[72:73], v[36:37], v[166:167] op_sel:[0,1] op_sel_hi:[1,1]
	v_pk_mul_f32 v[74:75], v[38:39], v[166:167] op_sel:[0,1] op_sel_hi:[1,1]
	v_pk_mul_f32 v[76:77], v[68:69], v[84:85]
	v_pk_mul_f32 v[78:79], v[70:71], v[84:85]
	v_pk_mul_f32 v[80:81], v[72:73], v[84:85]
	v_pk_mul_f32 v[82:83], v[74:75], v[84:85]
	v_exp_f32_e32 v76, v76
	v_exp_f32_e32 v77, v77
	v_exp_f32_e32 v78, v78
	v_exp_f32_e32 v79, v79
	v_exp_f32_e32 v80, v80
	v_exp_f32_e32 v81, v81
	v_exp_f32_e32 v82, v82
	v_exp_f32_e32 v83, v83
	v_pk_add_f32 v[76:77], v[76:77], v[86:87]
	v_pk_add_f32 v[78:79], v[78:79], v[86:87]
	v_pk_add_f32 v[80:81], v[80:81], v[86:87]
	v_pk_add_f32 v[82:83], v[82:83], v[86:87]
	v_rcp_f32_e32 v76, v76
	v_rcp_f32_e32 v77, v77
	v_rcp_f32_e32 v78, v78
	v_rcp_f32_e32 v79, v79
	v_rcp_f32_e32 v80, v80
	v_rcp_f32_e32 v81, v81
	v_rcp_f32_e32 v82, v82
	v_rcp_f32_e32 v83, v83
	v_cvt_pk_bf16_f32 v68, v76, v77
	v_cvt_pk_bf16_f32 v69, v78, v79
	v_cvt_pk_bf16_f32 v70, v80, v81
	v_cvt_pk_bf16_f32 v71, v82, v83
	global_store_dwordx4 v88, v[68:71], s[4:5] offset:768
	s_add_u32 s4, s4, 0x28000
	s_addc_u32 s5, s5, 0
	s_cmp_eq_u32 s48, 64
	s_cbranch_scc1 .Lsig_b_done
	v_pk_mul_f32 v[68:69], v[32:33], v[246:247] op_sel_hi:[1,0]
	v_pk_mul_f32 v[70:71], v[34:35], v[246:247] op_sel_hi:[1,0]
	v_pk_mul_f32 v[72:73], v[28:29], v[246:247] op_sel_hi:[1,0]
	v_pk_mul_f32 v[74:75], v[30:31], v[246:247] op_sel_hi:[1,0]
	v_pk_mul_f32 v[76:77], v[68:69], v[84:85]
	v_pk_mul_f32 v[78:79], v[70:71], v[84:85]
	v_pk_mul_f32 v[80:81], v[72:73], v[84:85]
	v_pk_mul_f32 v[82:83], v[74:75], v[84:85]
	v_exp_f32_e32 v76, v76
	v_exp_f32_e32 v77, v77
	v_exp_f32_e32 v78, v78
	v_exp_f32_e32 v79, v79
	v_exp_f32_e32 v80, v80
	v_exp_f32_e32 v81, v81
	v_exp_f32_e32 v82, v82
	v_exp_f32_e32 v83, v83
	v_pk_add_f32 v[76:77], v[76:77], v[86:87]
	v_pk_add_f32 v[78:79], v[78:79], v[86:87]
	v_pk_add_f32 v[80:81], v[80:81], v[86:87]
	v_pk_add_f32 v[82:83], v[82:83], v[86:87]
	v_rcp_f32_e32 v76, v76
	v_rcp_f32_e32 v77, v77
	v_rcp_f32_e32 v78, v78
	v_rcp_f32_e32 v79, v79
	v_rcp_f32_e32 v80, v80
	v_rcp_f32_e32 v81, v81
	v_rcp_f32_e32 v82, v82
	v_rcp_f32_e32 v83, v83
	v_cvt_pk_bf16_f32 v68, v76, v77
	v_cvt_pk_bf16_f32 v69, v78, v79
	v_cvt_pk_bf16_f32 v70, v80, v81
	v_cvt_pk_bf16_f32 v71, v82, v83
	global_store_dwordx4 v88, v[68:71], s[4:5] offset:768
	s_add_u32 s4, s4, 0x8000
	s_addc_u32 s5, s5, 0
	v_pk_mul_f32 v[68:69], v[24:25], v[246:247] op_sel:[0,1] op_sel_hi:[1,1]
	v_pk_mul_f32 v[70:71], v[26:27], v[246:247] op_sel:[0,1] op_sel_hi:[1,1]
	v_pk_mul_f32 v[72:73], v[20:21], v[246:247] op_sel:[0,1] op_sel_hi:[1,1]
	v_pk_mul_f32 v[74:75], v[22:23], v[246:247] op_sel:[0,1] op_sel_hi:[1,1]
	v_pk_mul_f32 v[76:77], v[68:69], v[84:85]
	v_pk_mul_f32 v[78:79], v[70:71], v[84:85]
	v_pk_mul_f32 v[80:81], v[72:73], v[84:85]
	v_pk_mul_f32 v[82:83], v[74:75], v[84:85]
	v_exp_f32_e32 v76, v76
	v_exp_f32_e32 v77, v77
	v_exp_f32_e32 v78, v78
	v_exp_f32_e32 v79, v79
	v_exp_f32_e32 v80, v80
	v_exp_f32_e32 v81, v81
	v_exp_f32_e32 v82, v82
	v_exp_f32_e32 v83, v83
	v_pk_add_f32 v[76:77], v[76:77], v[86:87]
	v_pk_add_f32 v[78:79], v[78:79], v[86:87]
	v_pk_add_f32 v[80:81], v[80:81], v[86:87]
	v_pk_add_f32 v[82:83], v[82:83], v[86:87]
	v_rcp_f32_e32 v76, v76
	v_rcp_f32_e32 v77, v77
	v_rcp_f32_e32 v78, v78
	v_rcp_f32_e32 v79, v79
	v_rcp_f32_e32 v80, v80
	v_rcp_f32_e32 v81, v81
	v_rcp_f32_e32 v82, v82
	v_rcp_f32_e32 v83, v83
	v_cvt_pk_bf16_f32 v68, v76, v77
	v_cvt_pk_bf16_f32 v69, v78, v79
	v_cvt_pk_bf16_f32 v70, v80, v81
	v_cvt_pk_bf16_f32 v71, v82, v83
	global_store_dwordx4 v88, v[68:71], s[4:5] offset:768
	s_add_u32 s4, s4, 0x8000
	s_addc_u32 s5, s5, 0
	v_pk_mul_f32 v[68:69], v[16:17], v[248:249] op_sel_hi:[1,0]
	v_pk_mul_f32 v[70:71], v[18:19], v[248:249] op_sel_hi:[1,0]
	v_pk_mul_f32 v[72:73], v[12:13], v[248:249] op_sel_hi:[1,0]
	v_pk_mul_f32 v[74:75], v[14:15], v[248:249] op_sel_hi:[1,0]
	v_pk_mul_f32 v[76:77], v[68:69], v[84:85]
	v_pk_mul_f32 v[78:79], v[70:71], v[84:85]
	v_pk_mul_f32 v[80:81], v[72:73], v[84:85]
	v_pk_mul_f32 v[82:83], v[74:75], v[84:85]
	v_exp_f32_e32 v76, v76
	v_exp_f32_e32 v77, v77
	v_exp_f32_e32 v78, v78
	v_exp_f32_e32 v79, v79
	v_exp_f32_e32 v80, v80
	v_exp_f32_e32 v81, v81
	v_exp_f32_e32 v82, v82
	v_exp_f32_e32 v83, v83
	v_pk_add_f32 v[76:77], v[76:77], v[86:87]
	v_pk_add_f32 v[78:79], v[78:79], v[86:87]
	v_pk_add_f32 v[80:81], v[80:81], v[86:87]
	v_pk_add_f32 v[82:83], v[82:83], v[86:87]
	v_rcp_f32_e32 v76, v76
	v_rcp_f32_e32 v77, v77
	v_rcp_f32_e32 v78, v78
	v_rcp_f32_e32 v79, v79
	v_rcp_f32_e32 v80, v80
	v_rcp_f32_e32 v81, v81
	v_rcp_f32_e32 v82, v82
	v_rcp_f32_e32 v83, v83
	v_cvt_pk_bf16_f32 v68, v76, v77
	v_cvt_pk_bf16_f32 v69, v78, v79
	v_cvt_pk_bf16_f32 v70, v80, v81
	v_cvt_pk_bf16_f32 v71, v82, v83
	global_store_dwordx4 v88, v[68:71], s[4:5] offset:768
	s_add_u32 s4, s4, 0x8000
	s_addc_u32 s5, s5, 0
	v_pk_mul_f32 v[68:69], v[8:9], v[248:249] op_sel:[0,1] op_sel_hi:[1,1]
	v_pk_mul_f32 v[70:71], v[10:11], v[248:249] op_sel:[0,1] op_sel_hi:[1,1]
	v_pk_mul_f32 v[72:73], v[4:5], v[248:249] op_sel:[0,1] op_sel_hi:[1,1]
	v_pk_mul_f32 v[74:75], v[6:7], v[248:249] op_sel:[0,1] op_sel_hi:[1,1]
	v_pk_mul_f32 v[76:77], v[68:69], v[84:85]
	v_pk_mul_f32 v[78:79], v[70:71], v[84:85]
	v_pk_mul_f32 v[80:81], v[72:73], v[84:85]
	v_pk_mul_f32 v[82:83], v[74:75], v[84:85]
	v_exp_f32_e32 v76, v76
	v_exp_f32_e32 v77, v77
	v_exp_f32_e32 v78, v78
	v_exp_f32_e32 v79, v79
	v_exp_f32_e32 v80, v80
	v_exp_f32_e32 v81, v81
	v_exp_f32_e32 v82, v82
	v_exp_f32_e32 v83, v83
	v_pk_add_f32 v[76:77], v[76:77], v[86:87]
	v_pk_add_f32 v[78:79], v[78:79], v[86:87]
	v_pk_add_f32 v[80:81], v[80:81], v[86:87]
	v_pk_add_f32 v[82:83], v[82:83], v[86:87]
	v_rcp_f32_e32 v76, v76
	v_rcp_f32_e32 v77, v77
	v_rcp_f32_e32 v78, v78
	v_rcp_f32_e32 v79, v79
	v_rcp_f32_e32 v80, v80
	v_rcp_f32_e32 v81, v81
	v_rcp_f32_e32 v82, v82
	v_rcp_f32_e32 v83, v83
	v_cvt_pk_bf16_f32 v68, v76, v77
	v_cvt_pk_bf16_f32 v69, v78, v79
	v_cvt_pk_bf16_f32 v70, v80, v81
	v_cvt_pk_bf16_f32 v71, v82, v83
	global_store_dwordx4 v88, v[68:71], s[4:5] offset:768
.Lsig_b_done:
.LBB0_176:
	s_mov_b64 s[2:3], 0
